# k5/k12 FFN-up epilogue H stores with system scope (sc0 sc1, write-through) on top of best
# baseline (speedup 1.0000x reference)
.LBB5_12:
	s_lshl_b32 s13, s20, 8
	v_max_f32_e32 v120, v120, v120
	s_add_i32 s22, s13, s39
	v_max_f32_e32 v120, 0, v120
	v_max_f32_e32 v121, v121, v121
	v_max_f32_e32 v122, v122, v122
	s_ashr_i32 s23, s22, 31
	s_lshl_b32 s24, s53, 8
	v_mul_f32_e32 v152, v120, v120
	v_max_f32_e32 v120, v125, v125
	v_max_f32_e32 v121, 0, v121
	v_max_f32_e32 v122, 0, v122
	s_ashr_i32 s25, s24, 31
	s_lshl_b64 s[22:23], s[22:23], 13
	v_max_f32_e32 v124, v124, v124
	v_max_f32_e32 v120, 0, v120
	v_mul_f32_e32 v125, v121, v121
	v_max_f32_e32 v121, v126, v126
	v_mul_f32_e32 v126, v122, v122
	v_max_f32_e32 v122, v127, v127
	v_max_f32_e32 v123, v123, v123
	s_or_b64 s[24:25], s[24:25], s[6:7]
	v_lshl_add_u64 v[146:147], v[136:137], 0, s[22:23]
	v_max_f32_e32 v124, 0, v124
	v_mul_f32_e32 v120, v120, v120
	v_max_f32_e32 v121, 0, v121
	v_max_f32_e32 v122, 0, v122
	v_max_f32_e32 v123, 0, v123
	v_max_f32_e32 v112, v112, v112
	v_lshl_add_u64 v[146:147], s[24:25], 1, v[146:147]
	v_mul_f32_e32 v124, v124, v124
	v_mul_f32_e32 v121, v121, v121
	v_mul_f32_e32 v122, v122, v122
	v_mul_f32_e32 v123, v123, v123
	v_cvt_pk_bf16_f32 v120, v124, v120
	v_max_f32_e32 v112, 0, v112
	v_max_f32_e32 v113, v113, v113
	v_max_f32_e32 v114, v114, v114
	v_cvt_pk_bf16_f32 v121, v121, v122
	v_cvt_pk_bf16_f32 v122, v152, v125
	v_cvt_pk_bf16_f32 v123, v126, v123
	global_store_dwordx4 v[146:147], v[120:123], off sc0 sc1
	v_max_f32_e32 v113, 0, v113
	v_max_f32_e32 v114, 0, v114
	v_mul_f32_e32 v120, v112, v112
	v_max_f32_e32 v112, v117, v117
	v_max_f32_e32 v116, v116, v116
	v_max_f32_e32 v112, 0, v112
	v_mul_f32_e32 v117, v113, v113
	v_max_f32_e32 v113, v118, v118
	v_mul_f32_e32 v118, v114, v114
	v_max_f32_e32 v114, v119, v119
	v_max_f32_e32 v115, v115, v115
	v_max_f32_e32 v116, 0, v116
	v_mul_f32_e32 v112, v112, v112
	v_max_f32_e32 v113, 0, v113
	v_max_f32_e32 v114, 0, v114
	v_max_f32_e32 v115, 0, v115
	v_max_f32_e32 v104, v104, v104
	v_mul_f32_e32 v116, v116, v116
	v_mul_f32_e32 v113, v113, v113
	v_mul_f32_e32 v114, v114, v114
	v_mul_f32_e32 v115, v115, v115
	v_cvt_pk_bf16_f32 v112, v116, v112
	v_max_f32_e32 v104, 0, v104
	v_max_f32_e32 v105, v105, v105
	v_max_f32_e32 v106, v106, v106
	v_cvt_pk_bf16_f32 v113, v113, v114
	v_cvt_pk_bf16_f32 v114, v120, v117
	v_cvt_pk_bf16_f32 v115, v118, v115
	global_store_dwordx4 v[146:147], v[112:115], off offset:256 sc0 sc1
	v_max_f32_e32 v108, v108, v108
	v_max_f32_e32 v105, 0, v105
	v_mul_f32_e32 v112, v104, v104
	v_max_f32_e32 v104, v109, v109
	v_max_f32_e32 v106, 0, v106
	v_max_f32_e32 v108, 0, v108
	v_max_f32_e32 v104, 0, v104
	v_mul_f32_e32 v109, v105, v105
	v_max_f32_e32 v105, v110, v110
	v_mul_f32_e32 v110, v106, v106
	v_max_f32_e32 v106, v111, v111
	v_mul_f32_e32 v108, v108, v108
	v_mul_f32_e32 v104, v104, v104
	v_max_f32_e32 v105, 0, v105
	v_max_f32_e32 v106, 0, v106
	v_max_f32_e32 v107, v107, v107
	v_mul_f32_e32 v105, v105, v105
	v_max_f32_e32 v107, 0, v107
	v_mul_f32_e32 v106, v106, v106
	v_cvt_pk_bf16_f32 v104, v108, v104
	v_add_co_u32_e32 v108, vcc, s45, v146
	v_max_f32_e32 v96, v96, v96
	v_mul_f32_e32 v107, v107, v107
	v_cvt_pk_bf16_f32 v105, v105, v106
	v_cvt_pk_bf16_f32 v106, v112, v109
	v_addc_co_u32_e32 v109, vcc, 0, v147, vcc
	v_max_f32_e32 v96, 0, v96
	v_max_f32_e32 v97, v97, v97
	v_max_f32_e32 v98, v98, v98
	v_cvt_pk_bf16_f32 v107, v110, v107
	global_store_dwordx4 v[108:109], v[104:107], off sc0 sc1
	v_max_f32_e32 v97, 0, v97
	v_max_f32_e32 v98, 0, v98
	v_mul_f32_e32 v104, v96, v96
	v_max_f32_e32 v96, v101, v101
	v_max_f32_e32 v100, v100, v100
	v_max_f32_e32 v96, 0, v96
	v_mul_f32_e32 v101, v97, v97
	v_max_f32_e32 v97, v102, v102
	v_mul_f32_e32 v102, v98, v98
	v_max_f32_e32 v98, v103, v103
	v_max_f32_e32 v99, v99, v99
	v_max_f32_e32 v100, 0, v100
	v_mul_f32_e32 v96, v96, v96
	v_max_f32_e32 v97, 0, v97
	v_max_f32_e32 v98, 0, v98
	v_max_f32_e32 v99, 0, v99
	v_max_f32_e32 v88, v88, v88
	v_mul_f32_e32 v100, v100, v100
	v_mul_f32_e32 v97, v97, v97
	v_mul_f32_e32 v98, v98, v98
	v_mul_f32_e32 v99, v99, v99
	v_cvt_pk_bf16_f32 v96, v100, v96
	v_max_f32_e32 v88, 0, v88
	v_max_f32_e32 v89, v89, v89
	v_max_f32_e32 v90, v90, v90
	v_cvt_pk_bf16_f32 v97, v97, v98
	v_cvt_pk_bf16_f32 v98, v104, v101
	v_cvt_pk_bf16_f32 v99, v102, v99
	global_store_dwordx4 v[108:109], v[96:99], off offset:256 sc0 sc1
	v_max_f32_e32 v92, v92, v92
	v_max_f32_e32 v89, 0, v89
	v_mul_f32_e32 v96, v88, v88
	v_max_f32_e32 v88, v93, v93
	v_max_f32_e32 v90, 0, v90
	v_max_f32_e32 v92, 0, v92
	v_max_f32_e32 v88, 0, v88
	v_mul_f32_e32 v93, v89, v89
	v_max_f32_e32 v89, v94, v94
	v_mul_f32_e32 v94, v90, v90
	v_max_f32_e32 v90, v95, v95
	v_mul_f32_e32 v92, v92, v92
	v_mul_f32_e32 v88, v88, v88
	v_max_f32_e32 v89, 0, v89
	v_max_f32_e32 v90, 0, v90
	v_max_f32_e32 v91, v91, v91
	v_mul_f32_e32 v89, v89, v89
	v_max_f32_e32 v91, 0, v91
	v_mul_f32_e32 v90, v90, v90
	v_cvt_pk_bf16_f32 v88, v92, v88
	v_add_co_u32_e32 v92, vcc, s46, v146
	v_max_f32_e32 v80, v80, v80
	v_mul_f32_e32 v91, v91, v91
	v_cvt_pk_bf16_f32 v89, v89, v90
	v_cvt_pk_bf16_f32 v90, v96, v93
	v_addc_co_u32_e32 v93, vcc, 0, v147, vcc
	v_max_f32_e32 v80, 0, v80
	v_max_f32_e32 v81, v81, v81
	v_max_f32_e32 v82, v82, v82
	v_cvt_pk_bf16_f32 v91, v94, v91
	global_store_dwordx4 v[92:93], v[88:91], off sc0 sc1
	v_max_f32_e32 v81, 0, v81
	v_max_f32_e32 v82, 0, v82
	v_mul_f32_e32 v88, v80, v80
	v_max_f32_e32 v80, v85, v85
	v_max_f32_e32 v84, v84, v84
	v_max_f32_e32 v80, 0, v80
	v_mul_f32_e32 v85, v81, v81
	v_max_f32_e32 v81, v86, v86
	v_mul_f32_e32 v86, v82, v82
	v_max_f32_e32 v82, v87, v87
	v_max_f32_e32 v83, v83, v83
	v_max_f32_e32 v84, 0, v84
	v_mul_f32_e32 v80, v80, v80
	v_max_f32_e32 v81, 0, v81
	v_max_f32_e32 v82, 0, v82
	v_max_f32_e32 v83, 0, v83
	v_max_f32_e32 v72, v72, v72
	v_mul_f32_e32 v84, v84, v84
	v_mul_f32_e32 v81, v81, v81
	v_mul_f32_e32 v82, v82, v82
	v_mul_f32_e32 v83, v83, v83
	v_cvt_pk_bf16_f32 v80, v84, v80
	v_max_f32_e32 v72, 0, v72
	v_max_f32_e32 v73, v73, v73
	v_max_f32_e32 v74, v74, v74
	v_cvt_pk_bf16_f32 v81, v81, v82
	v_cvt_pk_bf16_f32 v82, v88, v85
	v_cvt_pk_bf16_f32 v83, v86, v83
	global_store_dwordx4 v[92:93], v[80:83], off offset:256 sc0 sc1
	v_max_f32_e32 v76, v76, v76
	v_max_f32_e32 v73, 0, v73
	v_mul_f32_e32 v80, v72, v72
	v_max_f32_e32 v72, v77, v77
	v_max_f32_e32 v74, 0, v74
	v_max_f32_e32 v76, 0, v76
	v_max_f32_e32 v72, 0, v72
	v_mul_f32_e32 v77, v73, v73
	v_max_f32_e32 v73, v78, v78
	v_mul_f32_e32 v78, v74, v74
	v_max_f32_e32 v74, v79, v79
	v_mul_f32_e32 v76, v76, v76
	v_mul_f32_e32 v72, v72, v72
	v_max_f32_e32 v73, 0, v73
	v_max_f32_e32 v74, 0, v74
	v_max_f32_e32 v75, v75, v75
	v_mul_f32_e32 v73, v73, v73
	v_max_f32_e32 v75, 0, v75
	v_mul_f32_e32 v74, v74, v74
	v_cvt_pk_bf16_f32 v72, v76, v72
	v_add_co_u32_e32 v76, vcc, s47, v146
	v_max_f32_e32 v64, v64, v64
	v_mul_f32_e32 v75, v75, v75
	v_cvt_pk_bf16_f32 v73, v73, v74
	v_cvt_pk_bf16_f32 v74, v80, v77
	v_addc_co_u32_e32 v77, vcc, 0, v147, vcc
	v_max_f32_e32 v64, 0, v64
	v_max_f32_e32 v65, v65, v65
	v_max_f32_e32 v66, v66, v66
	v_cvt_pk_bf16_f32 v75, v78, v75
	global_store_dwordx4 v[76:77], v[72:75], off sc0 sc1
	v_max_f32_e32 v65, 0, v65
	v_max_f32_e32 v66, 0, v66
	v_mul_f32_e32 v72, v64, v64
	v_max_f32_e32 v64, v69, v69
	v_max_f32_e32 v68, v68, v68
	v_max_f32_e32 v64, 0, v64
	v_mul_f32_e32 v69, v65, v65
	v_max_f32_e32 v65, v70, v70
	v_mul_f32_e32 v70, v66, v66
	v_max_f32_e32 v66, v71, v71
	v_max_f32_e32 v67, v67, v67
	v_max_f32_e32 v68, 0, v68
	v_mul_f32_e32 v64, v64, v64
	v_max_f32_e32 v65, 0, v65
	v_max_f32_e32 v66, 0, v66
	v_max_f32_e32 v67, 0, v67
	v_max_f32_e32 v56, v56, v56
	v_mul_f32_e32 v68, v68, v68
	v_mul_f32_e32 v65, v65, v65
	v_mul_f32_e32 v66, v66, v66
	v_mul_f32_e32 v67, v67, v67
	v_cvt_pk_bf16_f32 v64, v68, v64
	v_max_f32_e32 v56, 0, v56
	v_max_f32_e32 v57, v57, v57
	v_max_f32_e32 v58, v58, v58
	v_cvt_pk_bf16_f32 v65, v65, v66
	v_cvt_pk_bf16_f32 v66, v72, v69
	v_cvt_pk_bf16_f32 v67, v70, v67
	global_store_dwordx4 v[76:77], v[64:67], off offset:256 sc0 sc1
	v_max_f32_e32 v60, v60, v60
	v_max_f32_e32 v57, 0, v57
	v_mul_f32_e32 v64, v56, v56
	v_max_f32_e32 v56, v61, v61
	v_max_f32_e32 v58, 0, v58
	v_max_f32_e32 v60, 0, v60
	v_max_f32_e32 v56, 0, v56
	v_mul_f32_e32 v61, v57, v57
	v_max_f32_e32 v57, v62, v62
	v_mul_f32_e32 v62, v58, v58
	v_max_f32_e32 v58, v63, v63
	v_mul_f32_e32 v60, v60, v60
	v_mul_f32_e32 v56, v56, v56
	v_max_f32_e32 v57, 0, v57
	v_max_f32_e32 v58, 0, v58
	v_max_f32_e32 v59, v59, v59
	v_mul_f32_e32 v57, v57, v57
	v_max_f32_e32 v59, 0, v59
	v_mul_f32_e32 v58, v58, v58
	v_cvt_pk_bf16_f32 v56, v60, v56
	v_add_co_u32_e32 v60, vcc, s48, v146
	v_max_f32_e32 v48, v48, v48
	v_mul_f32_e32 v59, v59, v59
	v_cvt_pk_bf16_f32 v57, v57, v58
	v_cvt_pk_bf16_f32 v58, v64, v61
	v_addc_co_u32_e32 v61, vcc, 0, v147, vcc
	v_max_f32_e32 v48, 0, v48
	v_max_f32_e32 v49, v49, v49
	v_max_f32_e32 v50, v50, v50
	v_cvt_pk_bf16_f32 v59, v62, v59
	global_store_dwordx4 v[60:61], v[56:59], off sc0 sc1
	v_max_f32_e32 v49, 0, v49
	v_max_f32_e32 v50, 0, v50
	v_mul_f32_e32 v56, v48, v48
	v_max_f32_e32 v48, v53, v53
	v_max_f32_e32 v52, v52, v52
	v_max_f32_e32 v48, 0, v48
	v_mul_f32_e32 v53, v49, v49
	v_max_f32_e32 v49, v54, v54
	v_mul_f32_e32 v54, v50, v50
	v_max_f32_e32 v50, v55, v55
	v_max_f32_e32 v51, v51, v51
	v_max_f32_e32 v52, 0, v52
	v_mul_f32_e32 v48, v48, v48
	v_max_f32_e32 v49, 0, v49
	v_max_f32_e32 v50, 0, v50
	v_max_f32_e32 v51, 0, v51
	v_max_f32_e32 v40, v40, v40
	v_mul_f32_e32 v52, v52, v52
	v_mul_f32_e32 v49, v49, v49
	v_mul_f32_e32 v50, v50, v50
	v_mul_f32_e32 v51, v51, v51
	v_cvt_pk_bf16_f32 v48, v52, v48
	v_max_f32_e32 v40, 0, v40
	v_max_f32_e32 v41, v41, v41
	v_max_f32_e32 v42, v42, v42
	v_cvt_pk_bf16_f32 v49, v49, v50
	v_cvt_pk_bf16_f32 v50, v56, v53
	v_cvt_pk_bf16_f32 v51, v54, v51
	global_store_dwordx4 v[60:61], v[48:51], off offset:256 sc0 sc1
	v_max_f32_e32 v44, v44, v44
	v_max_f32_e32 v41, 0, v41
	v_mul_f32_e32 v48, v40, v40
	v_max_f32_e32 v40, v45, v45
	v_max_f32_e32 v42, 0, v42
	v_max_f32_e32 v44, 0, v44
	v_max_f32_e32 v40, 0, v40
	v_mul_f32_e32 v45, v41, v41
	v_max_f32_e32 v41, v46, v46
	v_mul_f32_e32 v46, v42, v42
	v_max_f32_e32 v42, v47, v47
	v_mul_f32_e32 v44, v44, v44
	v_mul_f32_e32 v40, v40, v40
	v_max_f32_e32 v41, 0, v41
	v_max_f32_e32 v42, 0, v42
	v_max_f32_e32 v43, v43, v43
	v_mul_f32_e32 v41, v41, v41
	v_max_f32_e32 v43, 0, v43
	v_mul_f32_e32 v42, v42, v42
	v_cvt_pk_bf16_f32 v40, v44, v40
	v_add_co_u32_e32 v44, vcc, s49, v146
	v_max_f32_e32 v32, v32, v32
	v_mul_f32_e32 v43, v43, v43
	v_cvt_pk_bf16_f32 v41, v41, v42
	v_cvt_pk_bf16_f32 v42, v48, v45
	v_addc_co_u32_e32 v45, vcc, 0, v147, vcc
	v_max_f32_e32 v32, 0, v32
	v_max_f32_e32 v33, v33, v33
	v_max_f32_e32 v34, v34, v34
	v_cvt_pk_bf16_f32 v43, v46, v43
	global_store_dwordx4 v[44:45], v[40:43], off sc0 sc1
	v_max_f32_e32 v33, 0, v33
	v_max_f32_e32 v34, 0, v34
	v_mul_f32_e32 v40, v32, v32
	v_max_f32_e32 v32, v37, v37
	v_max_f32_e32 v36, v36, v36
	v_max_f32_e32 v32, 0, v32
	v_mul_f32_e32 v37, v33, v33
	v_max_f32_e32 v33, v38, v38
	v_mul_f32_e32 v38, v34, v34
	v_max_f32_e32 v34, v39, v39
	v_max_f32_e32 v35, v35, v35
	v_max_f32_e32 v36, 0, v36
	v_mul_f32_e32 v32, v32, v32
	v_max_f32_e32 v33, 0, v33
	v_max_f32_e32 v34, 0, v34
	v_max_f32_e32 v35, 0, v35
	v_max_f32_e32 v24, v24, v24
	v_mul_f32_e32 v36, v36, v36
	v_mul_f32_e32 v33, v33, v33
	v_mul_f32_e32 v34, v34, v34
	v_mul_f32_e32 v35, v35, v35
	v_cvt_pk_bf16_f32 v32, v36, v32
	v_max_f32_e32 v24, 0, v24
	v_max_f32_e32 v25, v25, v25
	v_max_f32_e32 v26, v26, v26
	v_cvt_pk_bf16_f32 v33, v33, v34
	v_cvt_pk_bf16_f32 v34, v40, v37
	v_cvt_pk_bf16_f32 v35, v38, v35
	global_store_dwordx4 v[44:45], v[32:35], off offset:256 sc0 sc1
	v_max_f32_e32 v28, v28, v28
	v_max_f32_e32 v25, 0, v25
	v_mul_f32_e32 v32, v24, v24
	v_max_f32_e32 v24, v29, v29
	v_max_f32_e32 v26, 0, v26
	v_max_f32_e32 v28, 0, v28
	v_max_f32_e32 v24, 0, v24
	v_mul_f32_e32 v29, v25, v25
	v_max_f32_e32 v25, v30, v30
	v_mul_f32_e32 v30, v26, v26
	v_max_f32_e32 v26, v31, v31
	v_mul_f32_e32 v28, v28, v28
	v_mul_f32_e32 v24, v24, v24
	v_max_f32_e32 v25, 0, v25
	v_max_f32_e32 v26, 0, v26
	v_max_f32_e32 v27, v27, v27
	v_mul_f32_e32 v25, v25, v25
	v_max_f32_e32 v27, 0, v27
	v_mul_f32_e32 v26, v26, v26
	v_cvt_pk_bf16_f32 v24, v28, v24
	v_add_co_u32_e32 v28, vcc, s50, v146
	v_max_f32_e32 v16, v16, v16
	v_mul_f32_e32 v27, v27, v27
	v_cvt_pk_bf16_f32 v25, v25, v26
	v_cvt_pk_bf16_f32 v26, v32, v29
	v_addc_co_u32_e32 v29, vcc, 0, v147, vcc
	v_max_f32_e32 v16, 0, v16
	v_max_f32_e32 v17, v17, v17
	v_max_f32_e32 v18, v18, v18
	v_cvt_pk_bf16_f32 v27, v30, v27
	global_store_dwordx4 v[28:29], v[24:27], off sc0 sc1
	v_max_f32_e32 v17, 0, v17
	v_max_f32_e32 v18, 0, v18
	v_mul_f32_e32 v24, v16, v16
	v_max_f32_e32 v16, v21, v21
	v_max_f32_e32 v20, v20, v20
	v_max_f32_e32 v16, 0, v16
	v_mul_f32_e32 v21, v17, v17
	v_max_f32_e32 v17, v22, v22
	v_mul_f32_e32 v22, v18, v18
	v_max_f32_e32 v18, v23, v23
	v_max_f32_e32 v19, v19, v19
	v_max_f32_e32 v20, 0, v20
	v_mul_f32_e32 v16, v16, v16
	v_max_f32_e32 v17, 0, v17
	v_max_f32_e32 v18, 0, v18
	v_max_f32_e32 v19, 0, v19
	v_max_f32_e32 v8, v8, v8
	v_mul_f32_e32 v20, v20, v20
	v_mul_f32_e32 v17, v17, v17
	v_mul_f32_e32 v18, v18, v18
	v_mul_f32_e32 v19, v19, v19
	v_cvt_pk_bf16_f32 v16, v20, v16
	v_max_f32_e32 v8, 0, v8
	v_max_f32_e32 v9, v9, v9
	v_max_f32_e32 v10, v10, v10
	v_cvt_pk_bf16_f32 v17, v17, v18
	v_cvt_pk_bf16_f32 v18, v24, v21
	v_cvt_pk_bf16_f32 v19, v22, v19
	global_store_dwordx4 v[28:29], v[16:19], off offset:256 sc0 sc1
	v_max_f32_e32 v12, v12, v12
	v_max_f32_e32 v9, 0, v9
	v_mul_f32_e32 v16, v8, v8
	v_max_f32_e32 v8, v13, v13
	v_max_f32_e32 v10, 0, v10
	v_max_f32_e32 v12, 0, v12
	v_max_f32_e32 v8, 0, v8
	v_mul_f32_e32 v13, v9, v9
	v_max_f32_e32 v9, v14, v14
	v_mul_f32_e32 v14, v10, v10
	v_max_f32_e32 v10, v15, v15
	v_mul_f32_e32 v12, v12, v12
	v_mul_f32_e32 v8, v8, v8
	v_max_f32_e32 v9, 0, v9
	v_max_f32_e32 v10, 0, v10
	v_max_f32_e32 v11, v11, v11
	v_mul_f32_e32 v9, v9, v9
	v_max_f32_e32 v11, 0, v11
	v_mul_f32_e32 v10, v10, v10
	v_cvt_pk_bf16_f32 v8, v12, v8
	v_add_co_u32_e32 v12, vcc, s51, v146
	v_max_f32_e32 v0, v0, v0
	v_max_f32_e32 v1, v1, v1
	v_max_f32_e32 v2, v2, v2
	v_mul_f32_e32 v11, v11, v11
	v_cvt_pk_bf16_f32 v9, v9, v10
	v_cvt_pk_bf16_f32 v10, v16, v13
	v_addc_co_u32_e32 v13, vcc, 0, v147, vcc
	v_max_f32_e32 v0, 0, v0
	v_max_f32_e32 v1, 0, v1
	v_max_f32_e32 v2, 0, v2
	v_cvt_pk_bf16_f32 v11, v14, v11
	global_store_dwordx4 v[12:13], v[8:11], off sc0 sc1
	v_max_f32_e32 v3, v3, v3
	v_max_f32_e32 v4, v4, v4
	v_mul_f32_e32 v8, v0, v0
	v_max_f32_e32 v0, v5, v5
	v_mul_f32_e32 v5, v1, v1
	v_max_f32_e32 v1, v6, v6
	v_mul_f32_e32 v6, v2, v2
	v_max_f32_e32 v2, v7, v7
	v_max_f32_e32 v0, 0, v0
	v_max_f32_e32 v1, 0, v1
	v_max_f32_e32 v2, 0, v2
	v_max_f32_e32 v3, 0, v3
	v_max_f32_e32 v4, 0, v4
	v_mul_f32_e32 v0, v0, v0
	v_mul_f32_e32 v1, v1, v1
	v_mul_f32_e32 v2, v2, v2
	v_mul_f32_e32 v3, v3, v3
	v_mul_f32_e32 v4, v4, v4
	v_cvt_pk_bf16_f32 v0, v4, v0
	v_cvt_pk_bf16_f32 v1, v1, v2
	v_cvt_pk_bf16_f32 v2, v8, v5
	v_cvt_pk_bf16_f32 v3, v6, v3
	global_store_dwordx4 v[12:13], v[0:3], off offset:256 sc0 sc1
	s_andn2_b64 vcc, exec, s[4:5]
	s_mov_b64 s[4:5], -1
	s_cbranch_vccnz .LBB5_5
	s_andn2_b64 vcc, exec, s[8:9]
	s_cbranch_vccnz .LBB5_4
	s_barrier
	s_branch .LBB5_4

.LBB12_12:
	s_lshl_b32 s13, s20, 8
	v_max_f32_e32 v120, v120, v120
	s_add_i32 s22, s13, s40
	v_max_f32_e32 v120, 0, v120
	v_max_f32_e32 v121, v121, v121
	v_max_f32_e32 v122, v122, v122
	s_ashr_i32 s23, s22, 31
	s_lshl_b32 s20, s21, 8
	v_mul_f32_e32 v152, v120, v120
	v_max_f32_e32 v120, v125, v125
	v_max_f32_e32 v121, 0, v121
	v_max_f32_e32 v122, 0, v122
	s_ashr_i32 s21, s20, 31
	s_lshl_b64 s[22:23], s[22:23], 13
	v_max_f32_e32 v124, v124, v124
	v_max_f32_e32 v120, 0, v120
	v_mul_f32_e32 v125, v121, v121
	v_max_f32_e32 v121, v126, v126
	v_mul_f32_e32 v126, v122, v122
	v_max_f32_e32 v122, v127, v127
	v_max_f32_e32 v123, v123, v123
	s_or_b64 s[20:21], s[20:21], s[4:5]
	v_lshl_add_u64 v[146:147], v[136:137], 0, s[22:23]
	v_max_f32_e32 v124, 0, v124
	v_mul_f32_e32 v120, v120, v120
	v_max_f32_e32 v121, 0, v121
	v_max_f32_e32 v122, 0, v122
	v_max_f32_e32 v123, 0, v123
	v_max_f32_e32 v112, v112, v112
	v_lshl_add_u64 v[146:147], s[20:21], 1, v[146:147]
	v_mul_f32_e32 v124, v124, v124
	v_mul_f32_e32 v121, v121, v121
	v_mul_f32_e32 v122, v122, v122
	v_mul_f32_e32 v123, v123, v123
	v_cvt_pk_bf16_f32 v120, v124, v120
	v_max_f32_e32 v112, 0, v112
	v_max_f32_e32 v113, v113, v113
	v_max_f32_e32 v114, v114, v114
	v_cvt_pk_bf16_f32 v121, v121, v122
	v_cvt_pk_bf16_f32 v122, v152, v125
	v_cvt_pk_bf16_f32 v123, v126, v123
	global_store_dwordx4 v[146:147], v[120:123], off sc0 sc1
	v_max_f32_e32 v113, 0, v113
	v_max_f32_e32 v114, 0, v114
	v_mul_f32_e32 v120, v112, v112
	v_max_f32_e32 v112, v117, v117
	v_max_f32_e32 v116, v116, v116
	v_max_f32_e32 v112, 0, v112
	v_mul_f32_e32 v117, v113, v113
	v_max_f32_e32 v113, v118, v118
	v_mul_f32_e32 v118, v114, v114
	v_max_f32_e32 v114, v119, v119
	v_max_f32_e32 v115, v115, v115
	v_max_f32_e32 v116, 0, v116
	v_mul_f32_e32 v112, v112, v112
	v_max_f32_e32 v113, 0, v113
	v_max_f32_e32 v114, 0, v114
	v_max_f32_e32 v115, 0, v115
	v_max_f32_e32 v104, v104, v104
	v_mul_f32_e32 v116, v116, v116
	v_mul_f32_e32 v113, v113, v113
	v_mul_f32_e32 v114, v114, v114
	v_mul_f32_e32 v115, v115, v115
	v_cvt_pk_bf16_f32 v112, v116, v112
	v_max_f32_e32 v104, 0, v104
	v_max_f32_e32 v105, v105, v105
	v_max_f32_e32 v106, v106, v106
	v_cvt_pk_bf16_f32 v113, v113, v114
	v_cvt_pk_bf16_f32 v114, v120, v117
	v_cvt_pk_bf16_f32 v115, v118, v115
	global_store_dwordx4 v[146:147], v[112:115], off offset:256 sc0 sc1
	v_max_f32_e32 v108, v108, v108
	v_max_f32_e32 v105, 0, v105
	v_mul_f32_e32 v112, v104, v104
	v_max_f32_e32 v104, v109, v109
	v_max_f32_e32 v106, 0, v106
	v_max_f32_e32 v108, 0, v108
	v_max_f32_e32 v104, 0, v104
	v_mul_f32_e32 v109, v105, v105
	v_max_f32_e32 v105, v110, v110
	v_mul_f32_e32 v110, v106, v106
	v_max_f32_e32 v106, v111, v111
	v_mul_f32_e32 v108, v108, v108
	v_mul_f32_e32 v104, v104, v104
	v_max_f32_e32 v105, 0, v105
	v_max_f32_e32 v106, 0, v106
	v_max_f32_e32 v107, v107, v107
	v_mul_f32_e32 v105, v105, v105
	v_max_f32_e32 v107, 0, v107
	v_mul_f32_e32 v106, v106, v106
	v_cvt_pk_bf16_f32 v104, v108, v104
	v_add_co_u32_e32 v108, vcc, s46, v146
	v_max_f32_e32 v96, v96, v96
	v_mul_f32_e32 v107, v107, v107
	v_cvt_pk_bf16_f32 v105, v105, v106
	v_cvt_pk_bf16_f32 v106, v112, v109
	v_addc_co_u32_e32 v109, vcc, 0, v147, vcc
	v_max_f32_e32 v96, 0, v96
	v_max_f32_e32 v97, v97, v97
	v_max_f32_e32 v98, v98, v98
	v_cvt_pk_bf16_f32 v107, v110, v107
	global_store_dwordx4 v[108:109], v[104:107], off sc0 sc1
	v_max_f32_e32 v97, 0, v97
	v_max_f32_e32 v98, 0, v98
	v_mul_f32_e32 v104, v96, v96
	v_max_f32_e32 v96, v101, v101
	v_max_f32_e32 v100, v100, v100
	v_max_f32_e32 v96, 0, v96
	v_mul_f32_e32 v101, v97, v97
	v_max_f32_e32 v97, v102, v102
	v_mul_f32_e32 v102, v98, v98
	v_max_f32_e32 v98, v103, v103
	v_max_f32_e32 v99, v99, v99
	v_max_f32_e32 v100, 0, v100
	v_mul_f32_e32 v96, v96, v96
	v_max_f32_e32 v97, 0, v97
	v_max_f32_e32 v98, 0, v98
	v_max_f32_e32 v99, 0, v99
	v_max_f32_e32 v88, v88, v88
	v_mul_f32_e32 v100, v100, v100
	v_mul_f32_e32 v97, v97, v97
	v_mul_f32_e32 v98, v98, v98
	v_mul_f32_e32 v99, v99, v99
	v_cvt_pk_bf16_f32 v96, v100, v96
	v_max_f32_e32 v88, 0, v88
	v_max_f32_e32 v89, v89, v89
	v_max_f32_e32 v90, v90, v90
	v_cvt_pk_bf16_f32 v97, v97, v98
	v_cvt_pk_bf16_f32 v98, v104, v101
	v_cvt_pk_bf16_f32 v99, v102, v99
	global_store_dwordx4 v[108:109], v[96:99], off offset:256 sc0 sc1
	v_max_f32_e32 v92, v92, v92
	v_max_f32_e32 v89, 0, v89
	v_mul_f32_e32 v96, v88, v88
	v_max_f32_e32 v88, v93, v93
	v_max_f32_e32 v90, 0, v90
	v_max_f32_e32 v92, 0, v92
	v_max_f32_e32 v88, 0, v88
	v_mul_f32_e32 v93, v89, v89
	v_max_f32_e32 v89, v94, v94
	v_mul_f32_e32 v94, v90, v90
	v_max_f32_e32 v90, v95, v95
	v_mul_f32_e32 v92, v92, v92
	v_mul_f32_e32 v88, v88, v88
	v_max_f32_e32 v89, 0, v89
	v_max_f32_e32 v90, 0, v90
	v_max_f32_e32 v91, v91, v91
	v_mul_f32_e32 v89, v89, v89
	v_max_f32_e32 v91, 0, v91
	v_mul_f32_e32 v90, v90, v90
	v_cvt_pk_bf16_f32 v88, v92, v88
	v_add_co_u32_e32 v92, vcc, s47, v146
	v_max_f32_e32 v80, v80, v80
	v_mul_f32_e32 v91, v91, v91
	v_cvt_pk_bf16_f32 v89, v89, v90
	v_cvt_pk_bf16_f32 v90, v96, v93
	v_addc_co_u32_e32 v93, vcc, 0, v147, vcc
	v_max_f32_e32 v80, 0, v80
	v_max_f32_e32 v81, v81, v81
	v_max_f32_e32 v82, v82, v82
	v_cvt_pk_bf16_f32 v91, v94, v91
	global_store_dwordx4 v[92:93], v[88:91], off sc0 sc1
	v_max_f32_e32 v81, 0, v81
	v_max_f32_e32 v82, 0, v82
	v_mul_f32_e32 v88, v80, v80
	v_max_f32_e32 v80, v85, v85
	v_max_f32_e32 v84, v84, v84
	v_max_f32_e32 v80, 0, v80
	v_mul_f32_e32 v85, v81, v81
	v_max_f32_e32 v81, v86, v86
	v_mul_f32_e32 v86, v82, v82
	v_max_f32_e32 v82, v87, v87
	v_max_f32_e32 v83, v83, v83
	v_max_f32_e32 v84, 0, v84
	v_mul_f32_e32 v80, v80, v80
	v_max_f32_e32 v81, 0, v81
	v_max_f32_e32 v82, 0, v82
	v_max_f32_e32 v83, 0, v83
	v_max_f32_e32 v72, v72, v72
	v_mul_f32_e32 v84, v84, v84
	v_mul_f32_e32 v81, v81, v81
	v_mul_f32_e32 v82, v82, v82
	v_mul_f32_e32 v83, v83, v83
	v_cvt_pk_bf16_f32 v80, v84, v80
	v_max_f32_e32 v72, 0, v72
	v_max_f32_e32 v73, v73, v73
	v_max_f32_e32 v74, v74, v74
	v_cvt_pk_bf16_f32 v81, v81, v82
	v_cvt_pk_bf16_f32 v82, v88, v85
	v_cvt_pk_bf16_f32 v83, v86, v83
	global_store_dwordx4 v[92:93], v[80:83], off offset:256 sc0 sc1
	v_max_f32_e32 v76, v76, v76
	v_max_f32_e32 v73, 0, v73
	v_mul_f32_e32 v80, v72, v72
	v_max_f32_e32 v72, v77, v77
	v_max_f32_e32 v74, 0, v74
	v_max_f32_e32 v76, 0, v76
	v_max_f32_e32 v72, 0, v72
	v_mul_f32_e32 v77, v73, v73
	v_max_f32_e32 v73, v78, v78
	v_mul_f32_e32 v78, v74, v74
	v_max_f32_e32 v74, v79, v79
	v_mul_f32_e32 v76, v76, v76
	v_mul_f32_e32 v72, v72, v72
	v_max_f32_e32 v73, 0, v73
	v_max_f32_e32 v74, 0, v74
	v_max_f32_e32 v75, v75, v75
	v_mul_f32_e32 v73, v73, v73
	v_max_f32_e32 v75, 0, v75
	v_mul_f32_e32 v74, v74, v74
	v_cvt_pk_bf16_f32 v72, v76, v72
	v_add_co_u32_e32 v76, vcc, s48, v146
	v_max_f32_e32 v64, v64, v64
	v_mul_f32_e32 v75, v75, v75
	v_cvt_pk_bf16_f32 v73, v73, v74
	v_cvt_pk_bf16_f32 v74, v80, v77
	v_addc_co_u32_e32 v77, vcc, 0, v147, vcc
	v_max_f32_e32 v64, 0, v64
	v_max_f32_e32 v65, v65, v65
	v_max_f32_e32 v66, v66, v66
	v_cvt_pk_bf16_f32 v75, v78, v75
	global_store_dwordx4 v[76:77], v[72:75], off sc0 sc1
	v_max_f32_e32 v65, 0, v65
	v_max_f32_e32 v66, 0, v66
	v_mul_f32_e32 v72, v64, v64
	v_max_f32_e32 v64, v69, v69
	v_max_f32_e32 v68, v68, v68
	v_max_f32_e32 v64, 0, v64
	v_mul_f32_e32 v69, v65, v65
	v_max_f32_e32 v65, v70, v70
	v_mul_f32_e32 v70, v66, v66
	v_max_f32_e32 v66, v71, v71
	v_max_f32_e32 v67, v67, v67
	v_max_f32_e32 v68, 0, v68
	v_mul_f32_e32 v64, v64, v64
	v_max_f32_e32 v65, 0, v65
	v_max_f32_e32 v66, 0, v66
	v_max_f32_e32 v67, 0, v67
	v_max_f32_e32 v56, v56, v56
	v_mul_f32_e32 v68, v68, v68
	v_mul_f32_e32 v65, v65, v65
	v_mul_f32_e32 v66, v66, v66
	v_mul_f32_e32 v67, v67, v67
	v_cvt_pk_bf16_f32 v64, v68, v64
	v_max_f32_e32 v56, 0, v56
	v_max_f32_e32 v57, v57, v57
	v_max_f32_e32 v58, v58, v58
	v_cvt_pk_bf16_f32 v65, v65, v66
	v_cvt_pk_bf16_f32 v66, v72, v69
	v_cvt_pk_bf16_f32 v67, v70, v67
	global_store_dwordx4 v[76:77], v[64:67], off offset:256 sc0 sc1
	v_max_f32_e32 v60, v60, v60
	v_max_f32_e32 v57, 0, v57
	v_mul_f32_e32 v64, v56, v56
	v_max_f32_e32 v56, v61, v61
	v_max_f32_e32 v58, 0, v58
	v_max_f32_e32 v60, 0, v60
	v_max_f32_e32 v56, 0, v56
	v_mul_f32_e32 v61, v57, v57
	v_max_f32_e32 v57, v62, v62
	v_mul_f32_e32 v62, v58, v58
	v_max_f32_e32 v58, v63, v63
	v_mul_f32_e32 v60, v60, v60
	v_mul_f32_e32 v56, v56, v56
	v_max_f32_e32 v57, 0, v57
	v_max_f32_e32 v58, 0, v58
	v_max_f32_e32 v59, v59, v59
	v_mul_f32_e32 v57, v57, v57
	v_max_f32_e32 v59, 0, v59
	v_mul_f32_e32 v58, v58, v58
	v_cvt_pk_bf16_f32 v56, v60, v56
	v_add_co_u32_e32 v60, vcc, s49, v146
	v_max_f32_e32 v48, v48, v48
	v_mul_f32_e32 v59, v59, v59
	v_cvt_pk_bf16_f32 v57, v57, v58
	v_cvt_pk_bf16_f32 v58, v64, v61
	v_addc_co_u32_e32 v61, vcc, 0, v147, vcc
	v_max_f32_e32 v48, 0, v48
	v_max_f32_e32 v49, v49, v49
	v_max_f32_e32 v50, v50, v50
	v_cvt_pk_bf16_f32 v59, v62, v59
	global_store_dwordx4 v[60:61], v[56:59], off sc0 sc1
	v_max_f32_e32 v49, 0, v49
	v_max_f32_e32 v50, 0, v50
	v_mul_f32_e32 v56, v48, v48
	v_max_f32_e32 v48, v53, v53
	v_max_f32_e32 v52, v52, v52
	v_max_f32_e32 v48, 0, v48
	v_mul_f32_e32 v53, v49, v49
	v_max_f32_e32 v49, v54, v54
	v_mul_f32_e32 v54, v50, v50
	v_max_f32_e32 v50, v55, v55
	v_max_f32_e32 v51, v51, v51
	v_max_f32_e32 v52, 0, v52
	v_mul_f32_e32 v48, v48, v48
	v_max_f32_e32 v49, 0, v49
	v_max_f32_e32 v50, 0, v50
	v_max_f32_e32 v51, 0, v51
	v_max_f32_e32 v40, v40, v40
	v_mul_f32_e32 v52, v52, v52
	v_mul_f32_e32 v49, v49, v49
	v_mul_f32_e32 v50, v50, v50
	v_mul_f32_e32 v51, v51, v51
	v_cvt_pk_bf16_f32 v48, v52, v48
	v_max_f32_e32 v40, 0, v40
	v_max_f32_e32 v41, v41, v41
	v_max_f32_e32 v42, v42, v42
	v_cvt_pk_bf16_f32 v49, v49, v50
	v_cvt_pk_bf16_f32 v50, v56, v53
	v_cvt_pk_bf16_f32 v51, v54, v51
	global_store_dwordx4 v[60:61], v[48:51], off offset:256 sc0 sc1
	v_max_f32_e32 v44, v44, v44
	v_max_f32_e32 v41, 0, v41
	v_mul_f32_e32 v48, v40, v40
	v_max_f32_e32 v40, v45, v45
	v_max_f32_e32 v42, 0, v42
	v_max_f32_e32 v44, 0, v44
	v_max_f32_e32 v40, 0, v40
	v_mul_f32_e32 v45, v41, v41
	v_max_f32_e32 v41, v46, v46
	v_mul_f32_e32 v46, v42, v42
	v_max_f32_e32 v42, v47, v47
	v_mul_f32_e32 v44, v44, v44
	v_mul_f32_e32 v40, v40, v40
	v_max_f32_e32 v41, 0, v41
	v_max_f32_e32 v42, 0, v42
	v_max_f32_e32 v43, v43, v43
	v_mul_f32_e32 v41, v41, v41
	v_max_f32_e32 v43, 0, v43
	v_mul_f32_e32 v42, v42, v42
	v_cvt_pk_bf16_f32 v40, v44, v40
	v_add_co_u32_e32 v44, vcc, s50, v146
	v_max_f32_e32 v32, v32, v32
	v_mul_f32_e32 v43, v43, v43
	v_cvt_pk_bf16_f32 v41, v41, v42
	v_cvt_pk_bf16_f32 v42, v48, v45
	v_addc_co_u32_e32 v45, vcc, 0, v147, vcc
	v_max_f32_e32 v32, 0, v32
	v_max_f32_e32 v33, v33, v33
	v_max_f32_e32 v34, v34, v34
	v_cvt_pk_bf16_f32 v43, v46, v43
	global_store_dwordx4 v[44:45], v[40:43], off sc0 sc1
	v_max_f32_e32 v33, 0, v33
	v_max_f32_e32 v34, 0, v34
	v_mul_f32_e32 v40, v32, v32
	v_max_f32_e32 v32, v37, v37
	v_max_f32_e32 v36, v36, v36
	v_max_f32_e32 v32, 0, v32
	v_mul_f32_e32 v37, v33, v33
	v_max_f32_e32 v33, v38, v38
	v_mul_f32_e32 v38, v34, v34
	v_max_f32_e32 v34, v39, v39
	v_max_f32_e32 v35, v35, v35
	v_max_f32_e32 v36, 0, v36
	v_mul_f32_e32 v32, v32, v32
	v_max_f32_e32 v33, 0, v33
	v_max_f32_e32 v34, 0, v34
	v_max_f32_e32 v35, 0, v35
	v_max_f32_e32 v24, v24, v24
	v_mul_f32_e32 v36, v36, v36
	v_mul_f32_e32 v33, v33, v33
	v_mul_f32_e32 v34, v34, v34
	v_mul_f32_e32 v35, v35, v35
	v_cvt_pk_bf16_f32 v32, v36, v32
	v_max_f32_e32 v24, 0, v24
	v_max_f32_e32 v25, v25, v25
	v_max_f32_e32 v26, v26, v26
	v_cvt_pk_bf16_f32 v33, v33, v34
	v_cvt_pk_bf16_f32 v34, v40, v37
	v_cvt_pk_bf16_f32 v35, v38, v35
	global_store_dwordx4 v[44:45], v[32:35], off offset:256 sc0 sc1
	v_max_f32_e32 v28, v28, v28
	v_max_f32_e32 v25, 0, v25
	v_mul_f32_e32 v32, v24, v24
	v_max_f32_e32 v24, v29, v29
	v_max_f32_e32 v26, 0, v26
	v_max_f32_e32 v28, 0, v28
	v_max_f32_e32 v24, 0, v24
	v_mul_f32_e32 v29, v25, v25
	v_max_f32_e32 v25, v30, v30
	v_mul_f32_e32 v30, v26, v26
	v_max_f32_e32 v26, v31, v31
	v_mul_f32_e32 v28, v28, v28
	v_mul_f32_e32 v24, v24, v24
	v_max_f32_e32 v25, 0, v25
	v_max_f32_e32 v26, 0, v26
	v_max_f32_e32 v27, v27, v27
	v_mul_f32_e32 v25, v25, v25
	v_max_f32_e32 v27, 0, v27
	v_mul_f32_e32 v26, v26, v26
	v_cvt_pk_bf16_f32 v24, v28, v24
	v_add_co_u32_e32 v28, vcc, s51, v146
	v_max_f32_e32 v16, v16, v16
	v_mul_f32_e32 v27, v27, v27
	v_cvt_pk_bf16_f32 v25, v25, v26
	v_cvt_pk_bf16_f32 v26, v32, v29
	v_addc_co_u32_e32 v29, vcc, 0, v147, vcc
	v_max_f32_e32 v16, 0, v16
	v_max_f32_e32 v17, v17, v17
	v_max_f32_e32 v18, v18, v18
	v_cvt_pk_bf16_f32 v27, v30, v27
	global_store_dwordx4 v[28:29], v[24:27], off sc0 sc1
	v_max_f32_e32 v17, 0, v17
	v_max_f32_e32 v18, 0, v18
	v_mul_f32_e32 v24, v16, v16
	v_max_f32_e32 v16, v21, v21
	v_max_f32_e32 v20, v20, v20
	v_max_f32_e32 v16, 0, v16
	v_mul_f32_e32 v21, v17, v17
	v_max_f32_e32 v17, v22, v22
	v_mul_f32_e32 v22, v18, v18
	v_max_f32_e32 v18, v23, v23
	v_max_f32_e32 v19, v19, v19
	v_max_f32_e32 v20, 0, v20
	v_mul_f32_e32 v16, v16, v16
	v_max_f32_e32 v17, 0, v17
	v_max_f32_e32 v18, 0, v18
	v_max_f32_e32 v19, 0, v19
	v_max_f32_e32 v8, v8, v8
	v_mul_f32_e32 v20, v20, v20
	v_mul_f32_e32 v17, v17, v17
	v_mul_f32_e32 v18, v18, v18
	v_mul_f32_e32 v19, v19, v19
	v_cvt_pk_bf16_f32 v16, v20, v16
	v_max_f32_e32 v8, 0, v8
	v_max_f32_e32 v9, v9, v9
	v_max_f32_e32 v10, v10, v10
	v_cvt_pk_bf16_f32 v17, v17, v18
	v_cvt_pk_bf16_f32 v18, v24, v21
	v_cvt_pk_bf16_f32 v19, v22, v19
	global_store_dwordx4 v[28:29], v[16:19], off offset:256 sc0 sc1
	v_max_f32_e32 v12, v12, v12
	v_max_f32_e32 v9, 0, v9
	v_mul_f32_e32 v16, v8, v8
	v_max_f32_e32 v8, v13, v13
	v_max_f32_e32 v10, 0, v10
	v_max_f32_e32 v12, 0, v12
	v_max_f32_e32 v8, 0, v8
	v_mul_f32_e32 v13, v9, v9
	v_max_f32_e32 v9, v14, v14
	v_mul_f32_e32 v14, v10, v10
	v_max_f32_e32 v10, v15, v15
	v_mul_f32_e32 v12, v12, v12
	v_mul_f32_e32 v8, v8, v8
	v_max_f32_e32 v9, 0, v9
	v_max_f32_e32 v10, 0, v10
	v_max_f32_e32 v11, v11, v11
	v_mul_f32_e32 v9, v9, v9
	v_max_f32_e32 v11, 0, v11
	v_mul_f32_e32 v10, v10, v10
	v_cvt_pk_bf16_f32 v8, v12, v8
	v_add_co_u32_e32 v12, vcc, s52, v146
	v_max_f32_e32 v0, v0, v0
	v_max_f32_e32 v1, v1, v1
	v_max_f32_e32 v2, v2, v2
	v_mul_f32_e32 v11, v11, v11
	v_cvt_pk_bf16_f32 v9, v9, v10
	v_cvt_pk_bf16_f32 v10, v16, v13
	v_addc_co_u32_e32 v13, vcc, 0, v147, vcc
	v_max_f32_e32 v0, 0, v0
	v_max_f32_e32 v1, 0, v1
	v_max_f32_e32 v2, 0, v2
	v_cvt_pk_bf16_f32 v11, v14, v11
	global_store_dwordx4 v[12:13], v[8:11], off sc0 sc1
	v_max_f32_e32 v3, v3, v3
	v_max_f32_e32 v4, v4, v4
	v_mul_f32_e32 v8, v0, v0
	v_max_f32_e32 v0, v5, v5
	v_mul_f32_e32 v5, v1, v1
	v_max_f32_e32 v1, v6, v6
	v_mul_f32_e32 v6, v2, v2
	v_max_f32_e32 v2, v7, v7
	v_max_f32_e32 v0, 0, v0
	v_max_f32_e32 v1, 0, v1
	v_max_f32_e32 v2, 0, v2
	v_max_f32_e32 v3, 0, v3
	v_max_f32_e32 v4, 0, v4
	v_mul_f32_e32 v0, v0, v0
	v_mul_f32_e32 v1, v1, v1
	v_mul_f32_e32 v2, v2, v2
	v_mul_f32_e32 v3, v3, v3
	v_mul_f32_e32 v4, v4, v4
	v_cvt_pk_bf16_f32 v0, v4, v0
	v_cvt_pk_bf16_f32 v1, v1, v2
	v_cvt_pk_bf16_f32 v2, v8, v5
	v_cvt_pk_bf16_f32 v3, v6, v3
	global_store_dwordx4 v[12:13], v[0:3], off offset:256 sc0 sc1
	s_mov_b64 s[20:21], -1
	s_mov_b64 vcc, s[0:1]
	s_cbranch_vccz .LBB12_5
	s_andn2_b64 vcc, exec, s[6:7]
	s_cbranch_vccnz .LBB12_4
	s_barrier
	s_branch .LBB12_4
